# P0 memn loop prefetches the next row; P8 SwiGLU epilogue rewritten by hand (same f32 arithmetic per element, no v_mov/v_pk_mul packing, rs-table LDS reads hoisted, chains interleaved stage by stage)
# speedup vs baseline: 1.0212x; 1.0029x over previous
; __device__ __forceinline__ unsigned pk2(float lo, float hi) { return pg8::cvt_pk_bf16(lo, hi); }
; __global__ void __launch_bounds__(NWAVES * 64, 2) mk_fwd(Args args) {
;     ...
;         for (int m = gw; m < NB * ML; m += NGW) {
;             const f32x4* xr = (const f32x4*)(mem + (size_t)m * DM) + lane;
;             f32x4 v[4]; float s = 0.f;
; #pragma unroll
;             for (int j = 0; j < 4; ++j) { v[j] = xr[64 * j]; s += (v[j][0] * v[j][0] + v[j][1] * v[j][1]) + (v[j][2] * v[j][2] + v[j][3] * v[j][3]); }
;             const float rs = 1.0f / sqrtf(wave_sum(s) * (1.f / DM) + EPS);
;             unsigned long long* o8 = (unsigned long long*)(MEMN + (size_t)m * DM) + lane;
; #pragma unroll
;             for (int j = 0; j < 4; ++j) { v[j] = v[j] * rs * gg[j]; o8[64 * j] = (unsigned long long)pk2(v[j][0], v[j][1]) | ((unsigned long long)pk2(v[j][2], v[j][3]) << 32); }
;         }
.LBB0_41:
	s_cmpk_gt_i32 s14, 0xfff
	s_cbranch_scc1 .LBB0_44
	v_mov_b32_e32 v177, 0
	v_lshl_add_u64 v[16:17], s[20:21], 0, v[176:177]
	flat_load_dwordx4 v[0:3], v[16:17]
	flat_load_dwordx4 v[4:7], v[16:17] offset:1024
	flat_load_dwordx4 v[8:11], v[16:17] offset:2048
	flat_load_dwordx4 v[12:15], v[16:17] offset:3072
	v_mbcnt_lo_u32_b32 v16, -1, 0
	v_mbcnt_hi_u32_b32 v16, -1, v16
	v_and_b32_e32 v17, 64, v16
	v_add_u32_e32 v17, 64, v17
	v_xor_b32_e32 v18, 1, v16
	v_cmp_lt_i32_e32 vcc, v18, v17
	s_ashr_i32 s15, s14, 31
	s_lshl_b64 s[4:5], s[14:15], 11
	v_cndmask_b32_e32 v18, v16, v18, vcc
	v_lshlrev_b32_e32 v20, 2, v18
	v_xor_b32_e32 v18, 2, v16
	v_cmp_lt_i32_e32 vcc, v18, v17
	s_add_u32 s4, s18, s4
	v_mov_b32_e32 v179, v177
	v_cndmask_b32_e32 v18, v16, v18, vcc
	v_lshlrev_b32_e32 v21, 2, v18
	v_xor_b32_e32 v18, 4, v16
	v_cmp_lt_i32_e32 vcc, v18, v17
	s_addc_u32 s5, s19, s5
	s_ashr_i32 s39, s38, 31
	v_cndmask_b32_e32 v18, v16, v18, vcc
	v_lshlrev_b32_e32 v22, 2, v18
	v_xor_b32_e32 v18, 8, v16
	v_cmp_lt_i32_e32 vcc, v18, v17
	s_lshl_b64 s[6:7], s[38:39], 11
	v_mov_b32_e32 v26, 0x358637bd
	v_cndmask_b32_e32 v18, v16, v18, vcc
	v_lshlrev_b32_e32 v23, 2, v18
	v_xor_b32_e32 v18, 16, v16
	v_cmp_lt_i32_e32 vcc, v18, v17
	s_mov_b32 s3, 0xf800000
	v_mov_b32_e32 v27, 0x260
	v_cndmask_b32_e32 v18, v16, v18, vcc
	v_lshlrev_b32_e32 v24, 2, v18
	v_xor_b32_e32 v18, 32, v16
	v_cmp_lt_i32_e32 vcc, v18, v17
	s_nop 1
	v_cndmask_b32_e32 v16, v16, v18, vcc
	v_lshlrev_b32_e32 v25, 2, v16
	v_lshl_add_u64 v[16:17], s[4:5], 0, v[178:179]
	s_mov_b64 s[4:5], 0x2600000
	v_lshl_add_u64 v[16:17], v[16:17], 0, s[4:5]
	s_lshl_b64 s[4:5], s[14:15], 12
	s_add_u32 s4, s16, s4
	s_addc_u32 s5, s17, s5
	v_lshl_add_u64 v[18:19], s[4:5], 0, v[176:177]
	s_lshl_b64 s[8:9], s[38:39], 12
	global_load_dwordx4 v[64:67], v[18:19], off
	global_load_dwordx4 v[68:71], v[18:19], off offset:1024
	global_load_dwordx4 v[72:75], v[18:19], off offset:2048
	global_load_dwordx4 v[76:79], v[18:19], off offset:3072
	s_waitcnt vmcnt(0) lgkmcnt(0)
.LBB0_43:
	s_waitcnt vmcnt(4)
	v_mov_b32_e32 v28, v64
	v_mov_b32_e32 v29, v65
	v_mov_b32_e32 v30, v66
	v_mov_b32_e32 v31, v67
	v_mov_b32_e32 v32, v68
	v_mov_b32_e32 v33, v69
	v_mov_b32_e32 v34, v70
	v_mov_b32_e32 v35, v71
	v_mov_b32_e32 v36, v72
	v_mov_b32_e32 v37, v73
	v_mov_b32_e32 v38, v74
	v_mov_b32_e32 v39, v75
	v_mov_b32_e32 v40, v76
	v_mov_b32_e32 v41, v77
	v_mov_b32_e32 v42, v78
	v_mov_b32_e32 v43, v79
	s_add_i32 s14, s14, s38
	v_lshl_add_u64 v[18:19], v[18:19], 0, s[8:9]
	s_cmpk_gt_i32 s14, 0xfff
	s_cbranch_scc1 .Lmemn_nopf
	global_load_dwordx4 v[64:67], v[18:19], off
	global_load_dwordx4 v[68:71], v[18:19], off offset:1024
	global_load_dwordx4 v[72:75], v[18:19], off offset:2048
	global_load_dwordx4 v[76:79], v[18:19], off offset:3072
.Lmemn_nopf:
	s_waitcnt lgkmcnt(0)
	v_pk_mul_f32 v[44:45], v[30:31], v[30:31]
	v_pk_mul_f32 v[46:47], v[28:29], v[28:29]
	v_pk_mul_f32 v[48:49], v[34:35], v[34:35]
	v_pk_mul_f32 v[50:51], v[32:33], v[32:33]
	v_pk_mov_b32 v[56:57], v[46:47], v[44:45] op_sel:[1,0]
	v_mov_b32_e32 v47, v45
	v_pk_mov_b32 v[44:45], v[50:51], v[48:49] op_sel:[1,0]
	v_mov_b32_e32 v51, v49
	v_mul_f32_e32 v55, v40, v40
	v_mul_f32_e32 v52, v37, v37
	v_mul_f32_e32 v54, v39, v39
	v_pk_add_f32 v[46:47], v[56:57], v[46:47]
	v_pk_add_f32 v[44:45], v[44:45], v[50:51]
	v_mul_f32_e32 v58, v41, v41
	v_mul_f32_e32 v59, v42, v42
	v_mul_f32_e32 v60, v43, v43
	v_pk_fma_f32 v[48:49], v[36:37], v[36:37], v[52:53] op_sel_hi:[1,1,0]
	v_pk_fma_f32 v[52:53], v[38:39], v[38:39], v[54:55] op_sel_hi:[1,1,0]
	v_pk_add_f32 v[46:47], v[46:47], v[46:47] op_sel:[0,1] op_sel_hi:[1,0]
	v_pk_add_f32 v[44:45], v[44:45], v[44:45] op_sel:[0,1] op_sel_hi:[1,0]
	v_mov_b32_e32 v49, v59
	v_mov_b32_e32 v53, v60
	v_mov_b32_e32 v47, v55
	v_mov_b32_e32 v45, v58
	v_pk_add_f32 v[48:49], v[48:49], v[52:53]
	v_pk_add_f32 v[44:45], v[46:47], v[44:45]
	s_nop 0
	v_pk_add_f32 v[44:45], v[44:45], v[48:49]
	s_nop 0
	v_add_f32_e32 v44, v44, v45
	ds_bpermute_b32 v45, v20, v44
	s_waitcnt lgkmcnt(0)
	v_add_f32_e32 v44, v44, v45
	ds_bpermute_b32 v45, v21, v44
	s_waitcnt lgkmcnt(0)
	v_add_f32_e32 v44, v44, v45
	ds_bpermute_b32 v45, v22, v44
	s_waitcnt lgkmcnt(0)
	v_add_f32_e32 v44, v44, v45
	ds_bpermute_b32 v45, v23, v44
	s_waitcnt lgkmcnt(0)
	v_add_f32_e32 v44, v44, v45
	ds_bpermute_b32 v45, v24, v44
	s_waitcnt lgkmcnt(0)
	v_add_f32_e32 v44, v44, v45
	ds_bpermute_b32 v45, v25, v44
	s_waitcnt lgkmcnt(0)
	v_add_f32_e32 v44, v44, v45
	v_fmamk_f32 v44, v44, 0x3a800000, v26
	v_mul_f32_e32 v45, 0x4f800000, v44
	v_cmp_gt_f32_e32 vcc, s3, v44
	s_nop 1
	v_cndmask_b32_e32 v44, v44, v45, vcc
	v_sqrt_f32_e32 v45, v44
	s_nop 0
	v_add_u32_e32 v46, -1, v45
	v_add_u32_e32 v47, 1, v45
	v_fma_f32 v48, -v46, v45, v44
	v_fma_f32 v49, -v47, v45, v44
	v_cmp_ge_f32_e64 s[4:5], 0, v48
	s_nop 1
	v_cndmask_b32_e64 v45, v45, v46, s[4:5]
	v_cmp_lt_f32_e64 s[4:5], 0, v49
	s_nop 1
	v_cndmask_b32_e64 v45, v45, v47, s[4:5]
	v_mul_f32_e32 v46, 0x37800000, v45
	v_cndmask_b32_e32 v45, v45, v46, vcc
	v_cmp_class_f32_e32 vcc, v44, v27
	s_nop 1
	v_cndmask_b32_e32 v44, v45, v44, vcc
	v_div_scale_f32 v45, s[4:5], v44, v44, 1.0
	v_rcp_f32_e32 v47, v45
	v_div_scale_f32 v46, vcc, 1.0, v44, 1.0
	v_fma_f32 v48, -v45, v47, 1.0
	v_fmac_f32_e32 v47, v48, v47
	v_mul_f32_e32 v48, v46, v47
	v_fma_f32 v49, -v45, v48, v46
	v_fmac_f32_e32 v48, v49, v47
	v_fma_f32 v45, -v45, v48, v46
	v_div_fmas_f32 v45, v45, v47, v48
	v_div_fixup_f32 v44, v45, v44, 1.0
	v_pk_mul_f32 v[28:29], v[44:45], v[28:29] op_sel_hi:[0,1]
	v_pk_mul_f32 v[30:31], v[44:45], v[30:31] op_sel_hi:[0,1]
	v_pk_mul_f32 v[28:29], v[28:29], v[0:1]
	v_pk_mul_f32 v[32:33], v[44:45], v[32:33] op_sel_hi:[0,1]
	v_pk_mul_f32 v[34:35], v[44:45], v[34:35] op_sel_hi:[0,1]
	v_pk_mul_f32 v[30:31], v[30:31], v[2:3]
	v_cvt_pk_bf16_f32 v28, v28, v29
	v_pk_mul_f32 v[36:37], v[44:45], v[36:37] op_sel_hi:[0,1]
	v_cvt_pk_bf16_f32 v29, v30, v31
	v_pk_mul_f32 v[38:39], v[44:45], v[38:39] op_sel_hi:[0,1]
	v_pk_mul_f32 v[34:35], v[34:35], v[6:7]
	v_pk_mul_f32 v[32:33], v[32:33], v[4:5]
	flat_store_dwordx2 v[16:17], v[28:29]
	v_cvt_pk_bf16_f32 v28, v32, v33
	v_cvt_pk_bf16_f32 v29, v34, v35
	v_pk_mul_f32 v[40:41], v[44:45], v[40:41] op_sel_hi:[0,1]
	v_pk_mul_f32 v[42:43], v[44:45], v[42:43] op_sel_hi:[0,1]
	v_pk_mul_f32 v[38:39], v[38:39], v[10:11]
	v_pk_mul_f32 v[36:37], v[36:37], v[8:9]
	flat_store_dwordx2 v[16:17], v[28:29] offset:512
	v_cvt_pk_bf16_f32 v28, v36, v37
	v_cvt_pk_bf16_f32 v29, v38, v39
	v_pk_mul_f32 v[42:43], v[42:43], v[14:15]
	v_pk_mul_f32 v[40:41], v[40:41], v[12:13]
	flat_store_dwordx2 v[16:17], v[28:29] offset:1024
	v_cvt_pk_bf16_f32 v28, v40, v41
	v_cvt_pk_bf16_f32 v29, v42, v43
	flat_store_dwordx2 v[16:17], v[28:29] offset:1536
	v_lshl_add_u64 v[16:17], v[16:17], 0, s[6:7]
	s_cbranch_scc0 .LBB0_43

; #define PG8_LAS __attribute__((address_space(3)))
; __device__ __forceinline__ u32x4 pack8(f32x4 v0, f32x4 v1) { u32x4 w; w.x = cvt_pk_bf16(v0[0], v0[1]); w.y = cvt_pk_bf16(v0[2], v0[3]); w.z = cvt_pk_bf16(v1[0], v1[1]); w.w = cvt_pk_bf16(v1[2], v1[3]); return w; }
;     __device__ __forceinline__ void operator()(Acc& acc, const Unit& u, int wr, int wc, int fr, int fq, PG8_LAS unsigned char* xl) const {
;         const PG8_LAS float* S = rs_table(SS, u.r0, xl);
; #pragma unroll
;         for (int ai = 0; ai < 2; ++ai)
; #pragma unroll
;             for (int m = 0; m < 4; ++m) { const int rl = ai * HALF + wr * 64 + m * 16 + fr; const int row = u.r0 + rl; const float s = S[rl], cs = -LOG2E * s, s2 = s * s;
;                 f32x4 o[2];
; #pragma unroll
;                 for (int n = 0; n < 2; ++n) { const f32x4 g = acc[ai][0][m][n], gu = acc[ai][0][m][n] * acc[ai][1][m][n]; f32x4 r;
; #pragma unroll
;                     for (int e = 0; e < 4; ++e) r[e] = gu[e] * (s2 * __builtin_amdgcn_rcpf(1.f + __builtin_amdgcn_exp2f(cs * g[e])));
;                     o[n] = r; }
;                 *(u32x4*)(H + (size_t)row * ldc + (u.c0 >> 1) + wc * 32 + 8 * fq) = pack8(o[0], o[1]); }
.Lrs8_skip:
	ds_read_b32 v184, v148
	ds_read_b32 v185, v150
	ds_read_b32 v186, v152
	ds_read_b32 v187, v155
	ds_read_b32 v188, v157
	ds_read_b32 v189, v159
	ds_read_b32 v190, v161
	ds_read_b32 v191, v163
	s_ashr_i32 s2, s33, 1
	s_ashr_i32 s3, s2, 31
	s_lshl_b64 s[2:3], s[2:3], 1
	s_andn2_b64 vcc, exec, s[6:7]
	v_mov_b64_e32 v[170:171], s[12:13]
	v_mul_f32_e32 v120, v124, v120
	v_mul_f32_e32 v121, v125, v121
	v_mul_f32_e32 v122, v126, v122
	v_mul_f32_e32 v123, v127, v123
	v_mul_f32_e32 v112, v116, v112
	v_mul_f32_e32 v113, v117, v113
	v_mul_f32_e32 v114, v118, v114
	v_mul_f32_e32 v115, v119, v115
	s_waitcnt lgkmcnt(0)
	v_mul_f32_e32 v174, 0xbfb8aa3b, v184
	v_mul_f32_e32 v175, v184, v184
	v_mul_f32_e32 v124, v124, v174
	v_mul_f32_e32 v125, v125, v174
	v_mul_f32_e32 v126, v126, v174
	v_mul_f32_e32 v127, v127, v174
	v_mul_f32_e32 v116, v116, v174
	v_mul_f32_e32 v117, v117, v174
	v_mul_f32_e32 v118, v118, v174
	v_mul_f32_e32 v119, v119, v174
	v_exp_f32_e32 v124, v124
	v_exp_f32_e32 v125, v125
	v_exp_f32_e32 v126, v126
	v_exp_f32_e32 v127, v127
	v_exp_f32_e32 v116, v116
	v_exp_f32_e32 v117, v117
	v_exp_f32_e32 v118, v118
	v_exp_f32_e32 v119, v119
	v_add_f32_e32 v124, 1.0, v124
	v_add_f32_e32 v125, 1.0, v125
	v_add_f32_e32 v126, 1.0, v126
	v_add_f32_e32 v127, 1.0, v127
	v_add_f32_e32 v116, 1.0, v116
	v_add_f32_e32 v117, 1.0, v117
	v_add_f32_e32 v118, 1.0, v118
	v_add_f32_e32 v119, 1.0, v119
	v_rcp_f32_e32 v124, v124
	v_rcp_f32_e32 v125, v125
	v_rcp_f32_e32 v126, v126
	v_rcp_f32_e32 v127, v127
	v_rcp_f32_e32 v116, v116
	v_rcp_f32_e32 v117, v117
	v_rcp_f32_e32 v118, v118
	v_rcp_f32_e32 v119, v119
	v_add_u32_e32 v172, s60, v146
	v_mad_i64_i32 v[172:173], s[30:31], v172, s64, v[170:171]
	v_lshl_add_u64 v[172:173], v[172:173], 0, s[2:3]
	v_lshl_add_u64 v[172:173], v[172:173], 0, s[8:9]
	v_lshl_add_u64 v[172:173], v[172:173], 0, v[136:137]
	v_mul_f32_e32 v124, v175, v124
	v_mul_f32_e32 v125, v175, v125
	v_mul_f32_e32 v126, v175, v126
	v_mul_f32_e32 v127, v175, v127
	v_mul_f32_e32 v116, v175, v116
	v_mul_f32_e32 v117, v175, v117
	v_mul_f32_e32 v118, v175, v118
	v_mul_f32_e32 v119, v175, v119
	v_mul_f32_e32 v120, v120, v124
	v_mul_f32_e32 v121, v121, v125
	v_mul_f32_e32 v122, v122, v126
	v_mul_f32_e32 v123, v123, v127
	v_mul_f32_e32 v112, v112, v116
	v_mul_f32_e32 v113, v113, v117
	v_mul_f32_e32 v114, v114, v118
	v_mul_f32_e32 v115, v115, v119
	v_cvt_pk_bf16_f32 v124, v120, v121
	v_cvt_pk_bf16_f32 v125, v122, v123
	v_cvt_pk_bf16_f32 v126, v112, v113
	v_cvt_pk_bf16_f32 v127, v114, v115
	flat_store_dwordx4 v[172:173], v[124:127]
	v_mul_f32_e32 v104, v108, v104
	v_mul_f32_e32 v105, v109, v105
	v_mul_f32_e32 v106, v110, v106
	v_mul_f32_e32 v107, v111, v107
	v_mul_f32_e32 v96, v100, v96
	v_mul_f32_e32 v97, v101, v97
	v_mul_f32_e32 v98, v102, v98
	v_mul_f32_e32 v99, v103, v99
	v_mul_f32_e32 v174, 0xbfb8aa3b, v185
	v_mul_f32_e32 v175, v185, v185
	v_mul_f32_e32 v108, v108, v174
	v_mul_f32_e32 v109, v109, v174
	v_mul_f32_e32 v110, v110, v174
	v_mul_f32_e32 v111, v111, v174
	v_mul_f32_e32 v100, v100, v174
	v_mul_f32_e32 v101, v101, v174
	v_mul_f32_e32 v102, v102, v174
	v_mul_f32_e32 v103, v103, v174
	v_exp_f32_e32 v108, v108
	v_exp_f32_e32 v109, v109
	v_exp_f32_e32 v110, v110
	v_exp_f32_e32 v111, v111
	v_exp_f32_e32 v100, v100
	v_exp_f32_e32 v101, v101
	v_exp_f32_e32 v102, v102
	v_exp_f32_e32 v103, v103
	v_add_f32_e32 v108, 1.0, v108
	v_add_f32_e32 v109, 1.0, v109
	v_add_f32_e32 v110, 1.0, v110
	v_add_f32_e32 v111, 1.0, v111
	v_add_f32_e32 v100, 1.0, v100
	v_add_f32_e32 v101, 1.0, v101
	v_add_f32_e32 v102, 1.0, v102
	v_add_f32_e32 v103, 1.0, v103
	v_rcp_f32_e32 v108, v108
	v_rcp_f32_e32 v109, v109
	v_rcp_f32_e32 v110, v110
	v_rcp_f32_e32 v111, v111
	v_rcp_f32_e32 v100, v100
	v_rcp_f32_e32 v101, v101
	v_rcp_f32_e32 v102, v102
	v_rcp_f32_e32 v103, v103
	v_add_u32_e32 v172, s60, v149
	v_mad_i64_i32 v[172:173], s[30:31], v172, s64, v[170:171]
	v_lshl_add_u64 v[172:173], v[172:173], 0, s[2:3]
	v_lshl_add_u64 v[172:173], v[172:173], 0, s[8:9]
	v_lshl_add_u64 v[172:173], v[172:173], 0, v[136:137]
	v_mul_f32_e32 v108, v175, v108
	v_mul_f32_e32 v109, v175, v109
	v_mul_f32_e32 v110, v175, v110
	v_mul_f32_e32 v111, v175, v111
	v_mul_f32_e32 v100, v175, v100
	v_mul_f32_e32 v101, v175, v101
	v_mul_f32_e32 v102, v175, v102
	v_mul_f32_e32 v103, v175, v103
	v_mul_f32_e32 v104, v104, v108
	v_mul_f32_e32 v105, v105, v109
	v_mul_f32_e32 v106, v106, v110
	v_mul_f32_e32 v107, v107, v111
	v_mul_f32_e32 v96, v96, v100
	v_mul_f32_e32 v97, v97, v101
	v_mul_f32_e32 v98, v98, v102
	v_mul_f32_e32 v99, v99, v103
	v_cvt_pk_bf16_f32 v108, v104, v105
	v_cvt_pk_bf16_f32 v109, v106, v107
	v_cvt_pk_bf16_f32 v110, v96, v97
	v_cvt_pk_bf16_f32 v111, v98, v99
	flat_store_dwordx4 v[172:173], v[108:111]
	v_mul_f32_e32 v88, v92, v88
	v_mul_f32_e32 v89, v93, v89
	v_mul_f32_e32 v90, v94, v90
	v_mul_f32_e32 v91, v95, v91
	v_mul_f32_e32 v80, v84, v80
	v_mul_f32_e32 v81, v85, v81
	v_mul_f32_e32 v82, v86, v82
	v_mul_f32_e32 v83, v87, v83
	v_mul_f32_e32 v174, 0xbfb8aa3b, v186
	v_mul_f32_e32 v175, v186, v186
	v_mul_f32_e32 v92, v92, v174
	v_mul_f32_e32 v93, v93, v174
	v_mul_f32_e32 v94, v94, v174
	v_mul_f32_e32 v95, v95, v174
	v_mul_f32_e32 v84, v84, v174
	v_mul_f32_e32 v85, v85, v174
	v_mul_f32_e32 v86, v86, v174
	v_mul_f32_e32 v87, v87, v174
	v_exp_f32_e32 v92, v92
	v_exp_f32_e32 v93, v93
	v_exp_f32_e32 v94, v94
	v_exp_f32_e32 v95, v95
	v_exp_f32_e32 v84, v84
	v_exp_f32_e32 v85, v85
	v_exp_f32_e32 v86, v86
	v_exp_f32_e32 v87, v87
	v_add_f32_e32 v92, 1.0, v92
	v_add_f32_e32 v93, 1.0, v93
	v_add_f32_e32 v94, 1.0, v94
	v_add_f32_e32 v95, 1.0, v95
	v_add_f32_e32 v84, 1.0, v84
	v_add_f32_e32 v85, 1.0, v85
; __device__ __forceinline__ u32x4 pack8(f32x4 v0, f32x4 v1) { u32x4 w; w.x = cvt_pk_bf16(v0[0], v0[1]); w.y = cvt_pk_bf16(v0[2], v0[3]); w.z = cvt_pk_bf16(v1[0], v1[1]); w.w = cvt_pk_bf16(v1[2], v1[3]); return w; }
;     __device__ __forceinline__ void operator()(Acc& acc, const Unit& u, int wr, int wc, int fr, int fq, PG8_LAS unsigned char* xl) const {
;     ...
;         for (int ai = 0; ai < 2; ++ai)
; #pragma unroll
;             for (int m = 0; m < 4; ++m) { const int rl = ai * HALF + wr * 64 + m * 16 + fr; const int row = u.r0 + rl; const float s = S[rl], cs = -LOG2E * s, s2 = s * s;
;                 f32x4 o[2];
; #pragma unroll
;                 for (int n = 0; n < 2; ++n) { const f32x4 g = acc[ai][0][m][n], gu = acc[ai][0][m][n] * acc[ai][1][m][n]; f32x4 r;
; #pragma unroll
;                     for (int e = 0; e < 4; ++e) r[e] = gu[e] * (s2 * __builtin_amdgcn_rcpf(1.f + __builtin_amdgcn_exp2f(cs * g[e])));
;                     o[n] = r; }
;                 *(u32x4*)(H + (size_t)row * ldc + (u.c0 >> 1) + wc * 32 + 8 * fq) = pack8(o[0], o[1]); }
	v_add_f32_e32 v86, 1.0, v86
	v_add_f32_e32 v87, 1.0, v87
	v_rcp_f32_e32 v92, v92
	v_rcp_f32_e32 v93, v93
	v_rcp_f32_e32 v94, v94
	v_rcp_f32_e32 v95, v95
	v_rcp_f32_e32 v84, v84
	v_rcp_f32_e32 v85, v85
	v_rcp_f32_e32 v86, v86
	v_rcp_f32_e32 v87, v87
	v_add_u32_e32 v172, s60, v151
	v_mad_i64_i32 v[172:173], s[30:31], v172, s64, v[170:171]
	v_lshl_add_u64 v[172:173], v[172:173], 0, s[2:3]
	v_lshl_add_u64 v[172:173], v[172:173], 0, s[8:9]
	v_lshl_add_u64 v[172:173], v[172:173], 0, v[136:137]
	v_mul_f32_e32 v92, v175, v92
	v_mul_f32_e32 v93, v175, v93
	v_mul_f32_e32 v94, v175, v94
	v_mul_f32_e32 v95, v175, v95
	v_mul_f32_e32 v84, v175, v84
	v_mul_f32_e32 v85, v175, v85
	v_mul_f32_e32 v86, v175, v86
	v_mul_f32_e32 v87, v175, v87
	v_mul_f32_e32 v88, v88, v92
	v_mul_f32_e32 v89, v89, v93
	v_mul_f32_e32 v90, v90, v94
	v_mul_f32_e32 v91, v91, v95
	v_mul_f32_e32 v80, v80, v84
	v_mul_f32_e32 v81, v81, v85
	v_mul_f32_e32 v82, v82, v86
	v_mul_f32_e32 v83, v83, v87
	v_cvt_pk_bf16_f32 v92, v88, v89
	v_cvt_pk_bf16_f32 v93, v90, v91
	v_cvt_pk_bf16_f32 v94, v80, v81
	v_cvt_pk_bf16_f32 v95, v82, v83
	flat_store_dwordx4 v[172:173], v[92:95]
	v_mul_f32_e32 v72, v76, v72
	v_mul_f32_e32 v73, v77, v73
	v_mul_f32_e32 v74, v78, v74
	v_mul_f32_e32 v75, v79, v75
	v_mul_f32_e32 v64, v68, v64
	v_mul_f32_e32 v65, v69, v65
	v_mul_f32_e32 v66, v70, v66
	v_mul_f32_e32 v67, v71, v67
	v_mul_f32_e32 v174, 0xbfb8aa3b, v187
	v_mul_f32_e32 v175, v187, v187
	v_mul_f32_e32 v76, v76, v174
	v_mul_f32_e32 v77, v77, v174
	v_mul_f32_e32 v78, v78, v174
	v_mul_f32_e32 v79, v79, v174
	v_mul_f32_e32 v68, v68, v174
	v_mul_f32_e32 v69, v69, v174
	v_mul_f32_e32 v70, v70, v174
	v_mul_f32_e32 v71, v71, v174
	v_exp_f32_e32 v76, v76
	v_exp_f32_e32 v77, v77
	v_exp_f32_e32 v78, v78
	v_exp_f32_e32 v79, v79
	v_exp_f32_e32 v68, v68
	v_exp_f32_e32 v69, v69
	v_exp_f32_e32 v70, v70
	v_exp_f32_e32 v71, v71
	v_add_f32_e32 v76, 1.0, v76
	v_add_f32_e32 v77, 1.0, v77
	v_add_f32_e32 v78, 1.0, v78
	v_add_f32_e32 v79, 1.0, v79
	v_add_f32_e32 v68, 1.0, v68
	v_add_f32_e32 v69, 1.0, v69
	v_add_f32_e32 v70, 1.0, v70
	v_add_f32_e32 v71, 1.0, v71
	v_rcp_f32_e32 v76, v76
	v_rcp_f32_e32 v77, v77
	v_rcp_f32_e32 v78, v78
	v_rcp_f32_e32 v79, v79
	v_rcp_f32_e32 v68, v68
	v_rcp_f32_e32 v69, v69
	v_rcp_f32_e32 v70, v70
	v_rcp_f32_e32 v71, v71
	v_add_u32_e32 v172, s60, v153
	v_mad_i64_i32 v[172:173], s[30:31], v172, s64, v[170:171]
	v_lshl_add_u64 v[172:173], v[172:173], 0, s[2:3]
	v_lshl_add_u64 v[172:173], v[172:173], 0, s[8:9]
	v_lshl_add_u64 v[172:173], v[172:173], 0, v[136:137]
	v_mul_f32_e32 v76, v175, v76
	v_mul_f32_e32 v77, v175, v77
	v_mul_f32_e32 v78, v175, v78
	v_mul_f32_e32 v79, v175, v79
	v_mul_f32_e32 v68, v175, v68
	v_mul_f32_e32 v69, v175, v69
	v_mul_f32_e32 v70, v175, v70
	v_mul_f32_e32 v71, v175, v71
	v_mul_f32_e32 v72, v72, v76
	v_mul_f32_e32 v73, v73, v77
	v_mul_f32_e32 v74, v74, v78
	v_mul_f32_e32 v75, v75, v79
	v_mul_f32_e32 v64, v64, v68
	v_mul_f32_e32 v65, v65, v69
	v_mul_f32_e32 v66, v66, v70
	v_mul_f32_e32 v67, v67, v71
	v_cvt_pk_bf16_f32 v76, v72, v73
	v_cvt_pk_bf16_f32 v77, v74, v75
	v_cvt_pk_bf16_f32 v78, v64, v65
	v_cvt_pk_bf16_f32 v79, v66, v67
	flat_store_dwordx4 v[172:173], v[76:79]
	v_mul_f32_e32 v56, v60, v56
	v_mul_f32_e32 v57, v61, v57
	v_mul_f32_e32 v58, v62, v58
	v_mul_f32_e32 v59, v63, v59
	v_mul_f32_e32 v48, v52, v48
	v_mul_f32_e32 v49, v53, v49
	v_mul_f32_e32 v50, v54, v50
	v_mul_f32_e32 v51, v55, v51
	v_mul_f32_e32 v174, 0xbfb8aa3b, v188
	v_mul_f32_e32 v175, v188, v188
	v_mul_f32_e32 v60, v60, v174
	v_mul_f32_e32 v61, v61, v174
	v_mul_f32_e32 v62, v62, v174
	v_mul_f32_e32 v63, v63, v174
	v_mul_f32_e32 v52, v52, v174
	v_mul_f32_e32 v53, v53, v174
	v_mul_f32_e32 v54, v54, v174
	v_mul_f32_e32 v55, v55, v174
	v_exp_f32_e32 v60, v60
	v_exp_f32_e32 v61, v61
	v_exp_f32_e32 v62, v62
	v_exp_f32_e32 v63, v63
	v_exp_f32_e32 v52, v52
	v_exp_f32_e32 v53, v53
	v_exp_f32_e32 v54, v54
	v_exp_f32_e32 v55, v55
	v_add_f32_e32 v60, 1.0, v60
	v_add_f32_e32 v61, 1.0, v61
	v_add_f32_e32 v62, 1.0, v62
	v_add_f32_e32 v63, 1.0, v63
	v_add_f32_e32 v52, 1.0, v52
	v_add_f32_e32 v53, 1.0, v53
	v_add_f32_e32 v54, 1.0, v54
	v_add_f32_e32 v55, 1.0, v55
	v_rcp_f32_e32 v60, v60
	v_rcp_f32_e32 v61, v61
	v_rcp_f32_e32 v62, v62
	v_rcp_f32_e32 v63, v63
	v_rcp_f32_e32 v52, v52
	v_rcp_f32_e32 v53, v53
	v_rcp_f32_e32 v54, v54
	v_rcp_f32_e32 v55, v55
	v_add_u32_e32 v172, s60, v156
	v_mad_i64_i32 v[172:173], s[30:31], v172, s64, v[170:171]
	v_lshl_add_u64 v[172:173], v[172:173], 0, s[2:3]
	v_lshl_add_u64 v[172:173], v[172:173], 0, s[8:9]
	v_lshl_add_u64 v[172:173], v[172:173], 0, v[136:137]
	v_mul_f32_e32 v60, v175, v60
	v_mul_f32_e32 v61, v175, v61
	v_mul_f32_e32 v62, v175, v62
	v_mul_f32_e32 v63, v175, v63
	v_mul_f32_e32 v52, v175, v52
	v_mul_f32_e32 v53, v175, v53
	v_mul_f32_e32 v54, v175, v54
	v_mul_f32_e32 v55, v175, v55
	v_mul_f32_e32 v56, v56, v60
	v_mul_f32_e32 v57, v57, v61
	v_mul_f32_e32 v58, v58, v62
	v_mul_f32_e32 v59, v59, v63
	v_mul_f32_e32 v48, v48, v52
	v_mul_f32_e32 v49, v49, v53
	v_mul_f32_e32 v50, v50, v54
	v_mul_f32_e32 v51, v51, v55
	v_cvt_pk_bf16_f32 v60, v56, v57
	v_cvt_pk_bf16_f32 v61, v58, v59
	v_cvt_pk_bf16_f32 v62, v48, v49
	v_cvt_pk_bf16_f32 v63, v50, v51
	flat_store_dwordx4 v[172:173], v[60:63]
	v_mul_f32_e32 v40, v44, v40
	v_mul_f32_e32 v41, v45, v41
	v_mul_f32_e32 v42, v46, v42
	v_mul_f32_e32 v43, v47, v43
	v_mul_f32_e32 v32, v36, v32
	v_mul_f32_e32 v33, v37, v33
	v_mul_f32_e32 v34, v38, v34
	v_mul_f32_e32 v35, v39, v35
	v_mul_f32_e32 v174, 0xbfb8aa3b, v189
	v_mul_f32_e32 v175, v189, v189
	v_mul_f32_e32 v44, v44, v174
	v_mul_f32_e32 v45, v45, v174
	v_mul_f32_e32 v46, v46, v174
; __device__ __forceinline__ u32x4 pack8(f32x4 v0, f32x4 v1) { u32x4 w; w.x = cvt_pk_bf16(v0[0], v0[1]); w.y = cvt_pk_bf16(v0[2], v0[3]); w.z = cvt_pk_bf16(v1[0], v1[1]); w.w = cvt_pk_bf16(v1[2], v1[3]); return w; }
;     __device__ __forceinline__ void operator()(Acc& acc, const Unit& u, int wr, int wc, int fr, int fq, PG8_LAS unsigned char* xl) const {
;     ...
;         for (int ai = 0; ai < 2; ++ai)
; #pragma unroll
;             for (int m = 0; m < 4; ++m) { const int rl = ai * HALF + wr * 64 + m * 16 + fr; const int row = u.r0 + rl; const float s = S[rl], cs = -LOG2E * s, s2 = s * s;
;                 f32x4 o[2];
; #pragma unroll
;                 for (int n = 0; n < 2; ++n) { const f32x4 g = acc[ai][0][m][n], gu = acc[ai][0][m][n] * acc[ai][1][m][n]; f32x4 r;
; #pragma unroll
;                     for (int e = 0; e < 4; ++e) r[e] = gu[e] * (s2 * __builtin_amdgcn_rcpf(1.f + __builtin_amdgcn_exp2f(cs * g[e])));
;                     o[n] = r; }
;                 *(u32x4*)(H + (size_t)row * ldc + (u.c0 >> 1) + wc * 32 + 8 * fq) = pack8(o[0], o[1]); }
	v_mul_f32_e32 v47, v47, v174
	v_mul_f32_e32 v36, v36, v174
	v_mul_f32_e32 v37, v37, v174
	v_mul_f32_e32 v38, v38, v174
	v_mul_f32_e32 v39, v39, v174
	v_exp_f32_e32 v44, v44
	v_exp_f32_e32 v45, v45
	v_exp_f32_e32 v46, v46
	v_exp_f32_e32 v47, v47
	v_exp_f32_e32 v36, v36
	v_exp_f32_e32 v37, v37
	v_exp_f32_e32 v38, v38
	v_exp_f32_e32 v39, v39
	v_add_f32_e32 v44, 1.0, v44
	v_add_f32_e32 v45, 1.0, v45
	v_add_f32_e32 v46, 1.0, v46
	v_add_f32_e32 v47, 1.0, v47
	v_add_f32_e32 v36, 1.0, v36
	v_add_f32_e32 v37, 1.0, v37
	v_add_f32_e32 v38, 1.0, v38
	v_add_f32_e32 v39, 1.0, v39
	v_rcp_f32_e32 v44, v44
	v_rcp_f32_e32 v45, v45
	v_rcp_f32_e32 v46, v46
	v_rcp_f32_e32 v47, v47
	v_rcp_f32_e32 v36, v36
	v_rcp_f32_e32 v37, v37
	v_rcp_f32_e32 v38, v38
	v_rcp_f32_e32 v39, v39
	v_add_u32_e32 v172, s60, v158
	v_mad_i64_i32 v[172:173], s[30:31], v172, s64, v[170:171]
	v_lshl_add_u64 v[172:173], v[172:173], 0, s[2:3]
	v_lshl_add_u64 v[172:173], v[172:173], 0, s[8:9]
	v_lshl_add_u64 v[172:173], v[172:173], 0, v[136:137]
	v_mul_f32_e32 v44, v175, v44
	v_mul_f32_e32 v45, v175, v45
	v_mul_f32_e32 v46, v175, v46
	v_mul_f32_e32 v47, v175, v47
	v_mul_f32_e32 v36, v175, v36
	v_mul_f32_e32 v37, v175, v37
	v_mul_f32_e32 v38, v175, v38
	v_mul_f32_e32 v39, v175, v39
	v_mul_f32_e32 v40, v40, v44
	v_mul_f32_e32 v41, v41, v45
	v_mul_f32_e32 v42, v42, v46
	v_mul_f32_e32 v43, v43, v47
	v_mul_f32_e32 v32, v32, v36
	v_mul_f32_e32 v33, v33, v37
	v_mul_f32_e32 v34, v34, v38
	v_mul_f32_e32 v35, v35, v39
	v_cvt_pk_bf16_f32 v44, v40, v41
	v_cvt_pk_bf16_f32 v45, v42, v43
	v_cvt_pk_bf16_f32 v46, v32, v33
	v_cvt_pk_bf16_f32 v47, v34, v35
	flat_store_dwordx4 v[172:173], v[44:47]
	v_mul_f32_e32 v24, v28, v24
	v_mul_f32_e32 v25, v29, v25
	v_mul_f32_e32 v26, v30, v26
	v_mul_f32_e32 v27, v31, v27
	v_mul_f32_e32 v16, v20, v16
	v_mul_f32_e32 v17, v21, v17
	v_mul_f32_e32 v18, v22, v18
	v_mul_f32_e32 v19, v23, v19
	v_mul_f32_e32 v174, 0xbfb8aa3b, v190
	v_mul_f32_e32 v175, v190, v190
	v_mul_f32_e32 v28, v28, v174
	v_mul_f32_e32 v29, v29, v174
	v_mul_f32_e32 v30, v30, v174
	v_mul_f32_e32 v31, v31, v174
	v_mul_f32_e32 v20, v20, v174
	v_mul_f32_e32 v21, v21, v174
	v_mul_f32_e32 v22, v22, v174
	v_mul_f32_e32 v23, v23, v174
	v_exp_f32_e32 v28, v28
	v_exp_f32_e32 v29, v29
	v_exp_f32_e32 v30, v30
	v_exp_f32_e32 v31, v31
	v_exp_f32_e32 v20, v20
	v_exp_f32_e32 v21, v21
	v_exp_f32_e32 v22, v22
	v_exp_f32_e32 v23, v23
	v_add_f32_e32 v28, 1.0, v28
	v_add_f32_e32 v29, 1.0, v29
	v_add_f32_e32 v30, 1.0, v30
	v_add_f32_e32 v31, 1.0, v31
	v_add_f32_e32 v20, 1.0, v20
	v_add_f32_e32 v21, 1.0, v21
	v_add_f32_e32 v22, 1.0, v22
	v_add_f32_e32 v23, 1.0, v23
	v_rcp_f32_e32 v28, v28
	v_rcp_f32_e32 v29, v29
	v_rcp_f32_e32 v30, v30
	v_rcp_f32_e32 v31, v31
	v_rcp_f32_e32 v20, v20
	v_rcp_f32_e32 v21, v21
	v_rcp_f32_e32 v22, v22
	v_rcp_f32_e32 v23, v23
	v_add_u32_e32 v172, s60, v160
	v_mad_i64_i32 v[172:173], s[30:31], v172, s64, v[170:171]
	v_lshl_add_u64 v[172:173], v[172:173], 0, s[2:3]
	v_lshl_add_u64 v[172:173], v[172:173], 0, s[8:9]
	v_lshl_add_u64 v[172:173], v[172:173], 0, v[136:137]
	v_mul_f32_e32 v28, v175, v28
	v_mul_f32_e32 v29, v175, v29
	v_mul_f32_e32 v30, v175, v30
	v_mul_f32_e32 v31, v175, v31
	v_mul_f32_e32 v20, v175, v20
	v_mul_f32_e32 v21, v175, v21
	v_mul_f32_e32 v22, v175, v22
	v_mul_f32_e32 v23, v175, v23
	v_mul_f32_e32 v24, v24, v28
	v_mul_f32_e32 v25, v25, v29
	v_mul_f32_e32 v26, v26, v30
	v_mul_f32_e32 v27, v27, v31
	v_mul_f32_e32 v16, v16, v20
	v_mul_f32_e32 v17, v17, v21
	v_mul_f32_e32 v18, v18, v22
	v_mul_f32_e32 v19, v19, v23
	v_cvt_pk_bf16_f32 v28, v24, v25
	v_cvt_pk_bf16_f32 v29, v26, v27
	v_cvt_pk_bf16_f32 v30, v16, v17
	v_cvt_pk_bf16_f32 v31, v18, v19
	flat_store_dwordx4 v[172:173], v[28:31]
	v_mul_f32_e32 v8, v12, v8
	v_mul_f32_e32 v9, v13, v9
	v_mul_f32_e32 v10, v14, v10
	v_mul_f32_e32 v11, v15, v11
	v_mul_f32_e32 v0, v4, v0
	v_mul_f32_e32 v1, v5, v1
	v_mul_f32_e32 v2, v6, v2
	v_mul_f32_e32 v3, v7, v3
	v_mul_f32_e32 v174, 0xbfb8aa3b, v191
	v_mul_f32_e32 v175, v191, v191
	v_mul_f32_e32 v12, v12, v174
	v_mul_f32_e32 v13, v13, v174
	v_mul_f32_e32 v14, v14, v174
	v_mul_f32_e32 v15, v15, v174
	v_mul_f32_e32 v4, v4, v174
	v_mul_f32_e32 v5, v5, v174
	v_mul_f32_e32 v6, v6, v174
	v_mul_f32_e32 v7, v7, v174
	v_exp_f32_e32 v12, v12
	v_exp_f32_e32 v13, v13
	v_exp_f32_e32 v14, v14
	v_exp_f32_e32 v15, v15
	v_exp_f32_e32 v4, v4
	v_exp_f32_e32 v5, v5
	v_exp_f32_e32 v6, v6
	v_exp_f32_e32 v7, v7
	v_add_f32_e32 v12, 1.0, v12
	v_add_f32_e32 v13, 1.0, v13
	v_add_f32_e32 v14, 1.0, v14
	v_add_f32_e32 v15, 1.0, v15
	v_add_f32_e32 v4, 1.0, v4
	v_add_f32_e32 v5, 1.0, v5
	v_add_f32_e32 v6, 1.0, v6
	v_add_f32_e32 v7, 1.0, v7
	v_rcp_f32_e32 v12, v12
	v_rcp_f32_e32 v13, v13
	v_rcp_f32_e32 v14, v14
	v_rcp_f32_e32 v15, v15
	v_rcp_f32_e32 v4, v4
	v_rcp_f32_e32 v5, v5
	v_rcp_f32_e32 v6, v6
	v_rcp_f32_e32 v7, v7
	v_add_u32_e32 v172, s60, v162
	v_mad_i64_i32 v[172:173], s[30:31], v172, s64, v[170:171]
	v_lshl_add_u64 v[172:173], v[172:173], 0, s[2:3]
	v_lshl_add_u64 v[172:173], v[172:173], 0, s[8:9]
	v_lshl_add_u64 v[172:173], v[172:173], 0, v[136:137]
	v_mul_f32_e32 v12, v175, v12
	v_mul_f32_e32 v13, v175, v13
	v_mul_f32_e32 v14, v175, v14
	v_mul_f32_e32 v15, v175, v15
	v_mul_f32_e32 v4, v175, v4
	v_mul_f32_e32 v5, v175, v5
	v_mul_f32_e32 v6, v175, v6
	v_mul_f32_e32 v7, v175, v7
	v_mul_f32_e32 v8, v8, v12
	v_mul_f32_e32 v9, v9, v13
	v_mul_f32_e32 v10, v10, v14
	v_mul_f32_e32 v11, v11, v15
	v_mul_f32_e32 v0, v0, v4
	v_mul_f32_e32 v1, v1, v5
	v_mul_f32_e32 v2, v2, v6
	v_mul_f32_e32 v3, v3, v7
	v_cvt_pk_bf16_f32 v12, v8, v9
	v_cvt_pk_bf16_f32 v13, v10, v11
	v_cvt_pk_bf16_f32 v14, v0, v1
	v_cvt_pk_bf16_f32 v15, v2, v3
	flat_store_dwordx4 v[172:173], v[12:15]
	s_mov_b64 s[2:3], -1
	s_cbranch_vccnz .LBB0_821
	s_andn2_b64 vcc, exec, s[10:11]
	s_cbranch_vccnz .LBB0_820
	s_barrier
	s_branch .LBB0_820
